# plus static s_setprio 1 for waves 0-3 during the attention phase
# baseline (speedup 1.0000x reference)
; __global__ void __launch_bounds__(NTHR) fwd_kernel(Args args) {
;     ...
;             { float a1 = lane < 32 ? ap->in[12][L * 32 + lane] * ap->in[13][L * 32 + lane] : 0.f, a2 = lane < 32 ? ap->in[14][L * 32 + lane] * ap->in[15][L * 32 + lane] : 0.f;
;               a1 = wave_sum(a1); a2 = wave_sum(a2); const float lv = __expf(a1) - __expf(a2) + (L == 0 ? ap->lam_init[0] : ap->lam_init[1]);
;               lam_u = __uint_as_float((unsigned)__builtin_amdgcn_readfirstlane((int)__float_as_uint(lv))); }
;             const bool pos_generic = __builtin_amdgcn_readfirstlane((int)__hip_atomic_load((const unsigned*)(ws + WS_POSFLAG), __ATOMIC_RELAXED, __HIP_MEMORY_SCOPE_AGENT)) != 0 || G > 1024;
;     ...
;                     if (tid == 0) *qslot = __hip_atomic_fetch_add(head, 1u, __ATOMIC_RELAXED, __HIP_MEMORY_SCOPE_AGENT);
;                     __syncthreads();
;                     const int idx = __builtin_amdgcn_readfirstlane((int)*qslot);
;                     __syncthreads();
;                     if (idx >= 1024) break;
;                     const int code = ap->order[idx], type = code >> 9, b = (code >> 8) & 1, h = (code >> 5) & 7, qb = code & 31;
.LBB0_149:
	s_or_b64 exec, exec, s[36:37]
	v_and_b32_e32 v0, 64, v216
	v_add_u32_e32 v0, 64, v0
	v_xor_b32_e32 v1, 1, v216
	v_cmp_lt_i32_e32 vcc, v1, v0
	s_add_i32 s4, s18, 10
	s_cmp_lt_u32 s4, 21
	v_cndmask_b32_e32 v1, v216, v1, vcc
	v_lshlrev_b32_e32 v193, 2, v1
	ds_bpermute_b32 v1, v193, v4
	s_movk_i32 s4, 0x128
	s_cselect_b32 s4, s4, 0x12c
	s_add_u32 s4, s0, s4
	s_addc_u32 s5, s1, 0
	s_waitcnt lgkmcnt(0)
	v_add_f32_e32 v1, v4, v1
	v_xor_b32_e32 v4, 2, v216
	v_cmp_lt_i32_e32 vcc, v4, v0
	s_load_dword s4, s[4:5], 0x0
	s_movk_i32 s5, 0x3000
	v_cndmask_b32_e32 v4, v216, v4, vcc
	v_lshlrev_b32_e32 v185, 2, v4
	ds_bpermute_b32 v4, v185, v1
	s_waitcnt lgkmcnt(0)
	v_sub_f32_e64 v224, 1.0, s4
	v_cmp_eq_u32_e64 s[40:41], 0, v192
	v_cmp_eq_u32_e64 s[42:43], 0, v216
	v_add_f32_e32 v1, v1, v4
	v_xor_b32_e32 v4, 4, v216
	v_cmp_lt_i32_e32 vcc, v4, v0
	s_nop 1
	v_cndmask_b32_e32 v4, v216, v4, vcc
	v_lshlrev_b32_e32 v220, 2, v4
	ds_bpermute_b32 v4, v220, v1
	s_waitcnt lgkmcnt(0)
	v_add_f32_e32 v1, v1, v4
	v_xor_b32_e32 v4, 8, v216
	v_cmp_lt_i32_e32 vcc, v4, v0
	s_nop 1
	v_cndmask_b32_e32 v4, v216, v4, vcc
	v_lshlrev_b32_e32 v221, 2, v4
	ds_bpermute_b32 v4, v221, v1
	s_waitcnt lgkmcnt(0)
	v_add_f32_e32 v1, v1, v4
	v_xor_b32_e32 v4, 16, v216
	v_cmp_lt_i32_e32 vcc, v4, v0
	s_nop 1
	v_cndmask_b32_e32 v4, v216, v4, vcc
	v_lshlrev_b32_e32 v222, 2, v4
	ds_bpermute_b32 v4, v222, v1
	s_waitcnt lgkmcnt(0)
	v_add_f32_e32 v1, v1, v4
	v_xor_b32_e32 v4, 32, v216
	v_cmp_lt_i32_e32 vcc, v4, v0
	s_nop 1
	v_cndmask_b32_e32 v0, v216, v4, vcc
	v_lshlrev_b32_e32 v223, 2, v0
	ds_bpermute_b32 v0, v223, v1
	s_waitcnt lgkmcnt(0)
	v_add_f32_e32 v0, v1, v0
	ds_bpermute_b32 v1, v193, v2
	v_mul_f32_e32 v0, 0x3fb8aa3b, v0
	v_exp_f32_e32 v0, v0
	s_waitcnt lgkmcnt(0)
	v_add_f32_e32 v1, v2, v1
	ds_bpermute_b32 v2, v185, v1
	s_waitcnt lgkmcnt(0)
	v_add_f32_e32 v1, v1, v2
	ds_bpermute_b32 v2, v220, v1
	s_waitcnt lgkmcnt(0)
	v_add_f32_e32 v1, v1, v2
	ds_bpermute_b32 v2, v221, v1
	s_waitcnt lgkmcnt(0)
	v_add_f32_e32 v1, v1, v2
	ds_bpermute_b32 v2, v222, v1
	s_waitcnt lgkmcnt(0)
	v_add_f32_e32 v1, v1, v2
	ds_bpermute_b32 v2, v223, v1
	s_waitcnt lgkmcnt(0)
	v_add_f32_e32 v1, v1, v2
	v_mul_f32_e32 v1, 0x3fb8aa3b, v1
	v_exp_f32_e32 v1, v1
	s_nop 0
	v_sub_f32_e32 v0, v0, v1
	v_add_f32_e32 v0, s4, v0
	v_mov_b32_e32 v1, s73
	v_readfirstlane_b32 s2, v0
	v_mov_b32_e32 v0, s72
	v_add_co_u32_e32 v0, vcc, s5, v0
	v_writelane_b32 v255, s2, 19
	s_nop 0
	v_addc_co_u32_e32 v1, vcc, 0, v1, vcc
	flat_load_dword v0, v[0:1] offset:3072 sc1
	s_waitcnt vmcnt(0) lgkmcnt(0)
	v_readfirstlane_b32 s5, v0
	s_cmp_eq_u32 s5, 0
	s_cselect_b64 s[18:19], -1, 0
	s_cmpk_lt_i32 s85, 0x401
	s_cselect_b64 s[26:27], -1, 0
	s_lshl_b32 s36, s10, 6
	s_and_b64 s[28:29], s[18:19], s[26:27]
	s_ashr_i32 s37, s36, 31
	s_add_u32 s5, s72, s36
	s_addc_u32 s6, s73, s37
	s_add_u32 s58, s5, 0x3800
	s_addc_u32 s59, s6, 0
	s_add_u32 s50, s72, 0x7400000
	s_addc_u32 s51, s73, 0
	s_add_u32 s25, s72, 0x7400400
	s_addc_u32 s52, s73, 0
	s_add_u32 s5, s72, 0x9400000
	v_writelane_b32 v255, s5, 17
	s_addc_u32 s5, s73, 0
	s_add_u32 s18, s72, 0xb100000
	s_addc_u32 s19, s73, 0
	s_ashr_i32 s11, s10, 31
	s_lshl_b64 s[38:39], s[10:11], 17
	s_add_u32 s64, s72, 0xc100000
	s_addc_u32 s65, s73, 0
	s_add_u32 s75, s72, 0xd900000
	s_addc_u32 s53, s73, 0
	s_add_u32 s2, s72, 0xb000000
	s_addc_u32 s92, s73, 0
	s_add_u32 s56, s72, 0xe900000
	s_addc_u32 s93, s73, 0
	s_add_u32 s62, s72, 0x6400000
	s_addc_u32 s63, s73, 0
	s_add_u32 s66, s72, 0xc0000
	s_addc_u32 s67, s73, 0
	v_writelane_b32 v255, s5, 18
	s_add_u32 s4, s72, s38
	v_writelane_b32 v255, s18, 20
	s_addc_u32 s5, s73, s39
	s_add_u32 s4, s4, 0x3340004
	v_writelane_b32 v255, s19, 21
	v_writelane_b32 v255, s4, 22
	s_addc_u32 s4, s5, 0
	v_writelane_b32 v255, s4, 23
	s_add_u32 s4, s54, 0x200
	v_writelane_b32 v255, s4, 24
	s_addc_u32 s4, s55, 0
	v_writelane_b32 v255, s4, 25
	s_lshl_b64 s[36:37], s[36:37], 2
	v_writelane_b32 v255, s25, 26
	v_writelane_b32 v255, s36, 27
	s_nop 1
	v_writelane_b32 v255, s37, 28
	v_readlane_b32 s99, v255, 8
	s_nop 3
	s_cmp_lt_u32 s99, 4
	s_cbranch_scc0 .Lprio_skip
	s_setprio 1
.Lprio_skip:
	s_branch .LBB0_154
.LBB0_150:
	v_exp_f32_e32 v0, v68
	v_exp_f32_e32 v52, v69
	v_exp_f32_e32 v1, v84
	v_exp_f32_e32 v60, v85
	v_exp_f32_e32 v53, v70
	v_exp_f32_e32 v61, v86
	v_exp_f32_e32 v54, v71
	v_exp_f32_e32 v62, v87
	v_exp_f32_e32 v55, v72
	v_exp_f32_e32 v63, v88
	v_exp_f32_e32 v56, v73
	v_exp_f32_e32 v64, v89
	v_exp_f32_e32 v57, v74
	v_exp_f32_e32 v65, v90
	v_exp_f32_e32 v58, v75
	v_exp_f32_e32 v66, v91
	v_exp_f32_e32 v59, v76
	v_exp_f32_e32 v67, v92
	v_exp_f32_e32 v68, v77
	v_exp_f32_e32 v69, v93
	v_exp_f32_e32 v70, v78
	v_exp_f32_e32 v71, v94
	v_exp_f32_e32 v72, v79
	v_exp_f32_e32 v73, v95
	v_exp_f32_e32 v74, v80
	v_exp_f32_e32 v75, v96
	v_exp_f32_e32 v76, v81
	v_exp_f32_e32 v77, v97
	v_exp_f32_e32 v78, v82
	v_exp_f32_e32 v79, v98
	v_exp_f32_e32 v80, v83
	v_exp_f32_e32 v81, v99
	v_cvt_pk_bf16_f32 v52, v0, v52
	v_add3_u32 v0, s12, v206, v199
	v_cvt_pk_bf16_f32 v60, v1, v60
	v_add_u32_e32 v1, 0x3000, v0
	v_cvt_pk_bf16_f32 v53, v53, v54
	v_cvt_pk_bf16_f32 v54, v55, v56
	v_cvt_pk_bf16_f32 v55, v57, v58
	v_cvt_pk_bf16_f32 v56, v59, v68
	v_cvt_pk_bf16_f32 v57, v70, v72
	v_cvt_pk_bf16_f32 v58, v74, v76
	v_cvt_pk_bf16_f32 v59, v78, v80
	v_cvt_pk_bf16_f32 v61, v61, v62
	v_cvt_pk_bf16_f32 v62, v63, v64
	v_cvt_pk_bf16_f32 v63, v65, v66
	v_cvt_pk_bf16_f32 v64, v67, v69
	v_cvt_pk_bf16_f32 v65, v71, v73
	v_cvt_pk_bf16_f32 v66, v75, v77
	v_cvt_pk_bf16_f32 v67, v79, v81
	ds_read2_b64 v[68:71], v1 offset0:128 offset1:130
	ds_read2_b64 v[72:75], v1 offset0:132 offset1:134
	ds_read2_b64 v[76:79], v1 offset0:136 offset1:138
	ds_read2_b64 v[80:83], v1 offset0:140 offset1:142
	s_waitcnt lgkmcnt(3)
	v_mfma_f32_32x32x16_bf16 v[4:19], v[68:71], v[52:55], v[4:19]
	s_waitcnt lgkmcnt(2)
	v_mfma_f32_32x32x16_bf16 v[4:19], v[72:75], v[56:59], v[4:19]
	s_waitcnt lgkmcnt(1)
	v_mfma_f32_32x32x16_bf16 v[4:19], v[76:79], v[60:63], v[4:19]
	s_waitcnt lgkmcnt(0)
	v_mfma_f32_32x32x16_bf16 v[4:19], v[80:83], v[64:67], v[4:19]
	v_add_u32_e32 v0, 0x4000, v0
	ds_read2_b64 v[68:71], v0 offset0:160 offset1:162
	ds_read2_b64 v[72:75], v0 offset0:164 offset1:166
	ds_read2_b64 v[76:79], v0 offset0:168 offset1:170
	ds_read2_b64 v[80:83], v0 offset0:172 offset1:174
	s_waitcnt lgkmcnt(3)
	v_mfma_f32_32x32x16_bf16 v[20:35], v[68:71], v[52:55], v[20:35]
	s_waitcnt lgkmcnt(2)
	v_mfma_f32_32x32x16_bf16 v[20:35], v[72:75], v[56:59], v[20:35]
	s_waitcnt lgkmcnt(1)
	v_mfma_f32_32x32x16_bf16 v[20:35], v[76:79], v[60:63], v[20:35]
	s_waitcnt lgkmcnt(0)
	v_mfma_f32_32x32x16_bf16 v[20:35], v[80:83], v[64:67], v[20:35]
	s_mov_b32 s69, s68
	s_mov_b32 s70, s68
	s_mov_b32 s71, s68
	v_mov_b64_e32 v[68:69], s[68:69]
	v_mov_b64_e32 v[70:71], s[70:71]
	s_nop 1
	v_mfma_f32_32x32x16_bf16 v[36:51], v[68:71], v[52:55], v[36:51]
	v_mfma_f32_32x32x16_bf16 v[36:51], v[68:71], v[56:59], v[36:51]
	v_mfma_f32_32x32x16_bf16 v[36:51], v[68:71], v[60:63], v[36:51]
	v_mfma_f32_32x32x16_bf16 v[36:51], v[68:71], v[64:67], v[36:51]

; #define LAS __attribute__((address_space(3)))
; #define MFMA32(a, b, c) __builtin_amdgcn_mfma_f32_32x32x16_bf16((a), (b), (c), 0, 0, 0)
; template <bool SUM> __device__ __forceinline__ bool softmax_tile(f32x16& pa, f32x16& pb, float& m, float& l, f32x16& o0, f32x16& o1, bool first) {
;     ...
; #pragma unroll
;     for (int r = 0; r < 16; ++r) { pa[r] = __builtin_amdgcn_exp2f(pa[r]); pb[r] = __builtin_amdgcn_exp2f(pb[r]); }
;     if (SUM) l += sum16(pa) + sum16(pb);
;     ...
;                 for (int ks = 0; ks < 4; ++ks) pf[mp][ks] = pack_frag(p[ks >> 1], ks & 1);
;             }
;             const LAS unsigned char* vb = bb + KB + r32 * VP + 8 * hi;
; #pragma unroll
;             for (int dh = 0; dh < 2; ++dh) {
;                 bf16x8 vf[4];
; #pragma unroll
;                 for (int ks = 0; ks < 4; ++ks) {
;                     const u32x2 v0 = *(const LAS u32x2*)(vb + dh * 32 * VP + 32 * ks), v1 = *(const LAS u32x2*)(vb + dh * 32 * VP + 32 * ks + 16);
;                     const u32x4 vv = {v0.x, v0.y, v1.x, v1.y}; vf[ks] = __builtin_bit_cast(bf16x8, vv); }
;                 __builtin_amdgcn_sched_barrier(0);
; #pragma unroll
;                 for (int ks = 0; ks < 4; ++ks)
; #pragma unroll
;                     for (int mp = 0; mp < NM; ++mp) o[mp][dh] = MFMA32(vf[ks], pf[mp][ks], o[mp][dh]);
.LBB0_199:
	s_or_b64 exec, exec, s[48:49]
	v_add3_u32 v0, s20, v232, v233
	v_add_u32_e32 v0, 0x2000, v0
	ds_read_b64 v[4:5], v0 offset:1024
	ds_read_b64 v[6:7], v0 offset:1040
	ds_read_b64 v[8:9], v0 offset:5376
	ds_read_b64 v[10:11], v0 offset:5392
	ds_read_b64 v[12:13], v0 offset:1056
	ds_read_b64 v[14:15], v0 offset:1072
	ds_read_b64 v[180:181], v0 offset:5408
	ds_read_b64 v[182:183], v0 offset:5424
	v_exp_f32_e32 v80, v80
	v_exp_f32_e32 v81, v81
	v_exp_f32_e32 v82, v82
	v_exp_f32_e32 v83, v83
	v_exp_f32_e32 v84, v84
	v_exp_f32_e32 v85, v85
	v_exp_f32_e32 v86, v86
	v_exp_f32_e32 v87, v87
	v_add_f32_e32 v0, v80, v81
	v_add_f32_e32 v1, v82, v83
	v_add_f32_e32 v0, v1, v0
	v_add_f32_e32 v1, v84, v85
	v_add_f32_e32 v2, v86, v87
	v_add_f32_e32 v1, v1, v2
	v_add_f32_e32 v176, v1, v0
	v_cvt_pk_bf16_f32 v80, v80, v81
	v_cvt_pk_bf16_f32 v81, v82, v83
	v_cvt_pk_bf16_f32 v82, v84, v85
	v_cvt_pk_bf16_f32 v83, v86, v87
	v_exp_f32_e32 v112, v112
	v_exp_f32_e32 v113, v113
	v_exp_f32_e32 v114, v114
	s_waitcnt lgkmcnt(4)
	v_mfma_f32_32x32x16_bf16 v[32:47], v[4:7], v[80:83], v[32:47]
	v_exp_f32_e32 v115, v115
	v_exp_f32_e32 v116, v116
	v_exp_f32_e32 v117, v117
	v_exp_f32_e32 v118, v118
	v_mfma_f32_32x32x16_bf16 v[64:79], v[8:11], v[80:83], v[64:79]
	v_exp_f32_e32 v119, v119
	v_add_f32_e32 v0, v112, v113
	v_add_f32_e32 v1, v114, v115
	v_add_f32_e32 v0, v1, v0
	v_add_f32_e32 v1, v116, v117
	v_add_f32_e32 v2, v118, v119
	v_add_f32_e32 v1, v1, v2
	v_add_f32_e32 v178, v1, v0
	v_cvt_pk_bf16_f32 v112, v112, v113
	v_cvt_pk_bf16_f32 v113, v114, v115
	v_cvt_pk_bf16_f32 v114, v116, v117
	v_cvt_pk_bf16_f32 v115, v118, v119
	v_exp_f32_e32 v88, v88
	v_exp_f32_e32 v89, v89
	v_exp_f32_e32 v90, v90
	v_mfma_f32_32x32x16_bf16 v[16:31], v[4:7], v[112:115], v[16:31]
	v_exp_f32_e32 v91, v91
	v_exp_f32_e32 v92, v92
	v_exp_f32_e32 v93, v93
	v_exp_f32_e32 v94, v94
	v_mfma_f32_32x32x16_bf16 v[48:63], v[8:11], v[112:115], v[48:63]
	v_exp_f32_e32 v95, v95
	v_add_f32_e32 v0, v88, v89
	v_add_f32_e32 v1, v90, v91
	v_add_f32_e32 v0, v1, v0
	v_add_f32_e32 v1, v92, v93
	v_add_f32_e32 v2, v94, v95
	v_add_f32_e32 v1, v1, v2
	v_add_f32_e32 v176, v0, v176
	v_add_f32_e32 v176, v1, v176
	v_cvt_pk_bf16_f32 v88, v88, v89
	v_cvt_pk_bf16_f32 v89, v90, v91
	v_cvt_pk_bf16_f32 v90, v92, v93
	v_cvt_pk_bf16_f32 v91, v94, v95
	v_add3_u32 v0, s20, v232, v233
	v_add_u32_e32 v0, 0x2000, v0
	ds_read_b64 v[4:5], v0 offset:1088
	ds_read_b64 v[6:7], v0 offset:1104
	ds_read_b64 v[8:9], v0 offset:5440
	ds_read_b64 v[10:11], v0 offset:5456
	v_exp_f32_e32 v120, v120
	v_exp_f32_e32 v121, v121
	v_exp_f32_e32 v122, v122
	s_waitcnt lgkmcnt(4)
	v_mfma_f32_32x32x16_bf16 v[32:47], v[12:15], v[88:91], v[32:47]
	v_exp_f32_e32 v123, v123
	v_exp_f32_e32 v124, v124
	v_exp_f32_e32 v125, v125
	v_exp_f32_e32 v126, v126
	v_mfma_f32_32x32x16_bf16 v[64:79], v[180:183], v[88:91], v[64:79]
	v_exp_f32_e32 v127, v127
	v_add_f32_e32 v0, v120, v121
	v_add_f32_e32 v1, v122, v123
	v_add_f32_e32 v0, v1, v0
	v_add_f32_e32 v1, v124, v125
	v_add_f32_e32 v2, v126, v127
	v_add_f32_e32 v1, v1, v2
	v_add_f32_e32 v178, v0, v178
	v_add_f32_e32 v178, v1, v178
	v_cvt_pk_bf16_f32 v120, v120, v121
	v_cvt_pk_bf16_f32 v121, v122, v123
	v_cvt_pk_bf16_f32 v122, v124, v125
	v_cvt_pk_bf16_f32 v123, v126, v127
	v_exp_f32_e32 v96, v96
	v_exp_f32_e32 v97, v97
	v_exp_f32_e32 v98, v98
	v_mfma_f32_32x32x16_bf16 v[16:31], v[12:15], v[120:123], v[16:31]
	v_exp_f32_e32 v99, v99
	v_exp_f32_e32 v100, v100
	v_exp_f32_e32 v101, v101
	v_exp_f32_e32 v102, v102
	v_mfma_f32_32x32x16_bf16 v[48:63], v[180:183], v[120:123], v[48:63]
	v_exp_f32_e32 v103, v103
	v_add_f32_e32 v0, v96, v97
	v_add_f32_e32 v1, v98, v99
	v_add_f32_e32 v0, v1, v0
	v_add_f32_e32 v1, v100, v101
	v_add_f32_e32 v2, v102, v103
	v_add_f32_e32 v1, v1, v2
	v_add_f32_e32 v177, v1, v0
	v_cvt_pk_bf16_f32 v96, v96, v97
	v_cvt_pk_bf16_f32 v97, v98, v99
	v_cvt_pk_bf16_f32 v98, v100, v101
	v_cvt_pk_bf16_f32 v99, v102, v103
	v_add3_u32 v0, s20, v232, v233
	v_add_u32_e32 v0, 0x2000, v0
	ds_read_b64 v[12:13], v0 offset:1120
	ds_read_b64 v[14:15], v0 offset:1136
	ds_read_b64 v[180:181], v0 offset:5472
	ds_read_b64 v[182:183], v0 offset:5488
	v_exp_f32_e32 v128, v128
	v_exp_f32_e32 v129, v129
	v_exp_f32_e32 v130, v130
	s_waitcnt lgkmcnt(4)
	v_mfma_f32_32x32x16_bf16 v[32:47], v[4:7], v[96:99], v[32:47]
	v_exp_f32_e32 v131, v131
	v_exp_f32_e32 v132, v132
	v_exp_f32_e32 v133, v133
	v_exp_f32_e32 v134, v134
	v_mfma_f32_32x32x16_bf16 v[64:79], v[8:11], v[96:99], v[64:79]
	v_exp_f32_e32 v135, v135
	v_add_f32_e32 v0, v128, v129
	v_add_f32_e32 v1, v130, v131
	v_add_f32_e32 v0, v1, v0
	v_add_f32_e32 v1, v132, v133
	v_add_f32_e32 v2, v134, v135
	v_add_f32_e32 v1, v1, v2
	v_add_f32_e32 v179, v1, v0
	v_cvt_pk_bf16_f32 v128, v128, v129
	v_cvt_pk_bf16_f32 v129, v130, v131
	v_cvt_pk_bf16_f32 v130, v132, v133
	v_cvt_pk_bf16_f32 v131, v134, v135
	v_exp_f32_e32 v104, v104
	v_exp_f32_e32 v105, v105
	v_exp_f32_e32 v106, v106
	v_mfma_f32_32x32x16_bf16 v[16:31], v[4:7], v[128:131], v[16:31]
	v_exp_f32_e32 v107, v107
	v_exp_f32_e32 v108, v108
	v_exp_f32_e32 v109, v109
	v_exp_f32_e32 v110, v110
	v_mfma_f32_32x32x16_bf16 v[48:63], v[8:11], v[128:131], v[48:63]
	v_exp_f32_e32 v111, v111
	v_add_f32_e32 v0, v104, v105
	v_add_f32_e32 v1, v106, v107
	v_add_f32_e32 v0, v1, v0
	v_add_f32_e32 v1, v108, v109
	v_add_f32_e32 v2, v110, v111
	v_add_f32_e32 v1, v1, v2
	v_add_f32_e32 v177, v0, v177
	v_add_f32_e32 v177, v1, v177
	v_add_f32_e32 v0, v177, v176
	v_add_f32_e32 v236, v236, v0
	v_cvt_pk_bf16_f32 v104, v104, v105
	v_cvt_pk_bf16_f32 v105, v106, v107
	v_cvt_pk_bf16_f32 v106, v108, v109
	v_cvt_pk_bf16_f32 v107, v110, v111
	v_exp_f32_e32 v136, v136
	v_exp_f32_e32 v137, v137
	v_exp_f32_e32 v138, v138
	s_waitcnt lgkmcnt(0)
	v_mfma_f32_32x32x16_bf16 v[32:47], v[12:15], v[104:107], v[32:47]
	v_exp_f32_e32 v139, v139
	v_exp_f32_e32 v140, v140
	v_exp_f32_e32 v141, v141
	v_exp_f32_e32 v142, v142
	v_mfma_f32_32x32x16_bf16 v[64:79], v[180:183], v[104:107], v[64:79]
	v_exp_f32_e32 v143, v143
	v_add_f32_e32 v0, v136, v137
	v_add_f32_e32 v1, v138, v139
	v_add_f32_e32 v0, v1, v0
	v_add_f32_e32 v1, v140, v141
	v_add_f32_e32 v2, v142, v143
	v_add_f32_e32 v1, v1, v2
	v_add_f32_e32 v179, v0, v179
	v_add_f32_e32 v179, v1, v179
	v_add_f32_e32 v0, v179, v178
	v_add_f32_e32 v228, v228, v0
	v_cvt_pk_bf16_f32 v136, v136, v137
	v_cvt_pk_bf16_f32 v137, v138, v139
	v_cvt_pk_bf16_f32 v138, v140, v141
	v_cvt_pk_bf16_f32 v139, v142, v143
	s_nop 1
	v_mfma_f32_32x32x16_bf16 v[16:31], v[12:15], v[136:139], v[16:31]
	v_mfma_f32_32x32x16_bf16 v[48:63], v[180:183], v[136:139], v[48:63]
	s_andn2_b64 vcc, exec, s[80:81]
	s_cbranch_vccnz .LBB0_175

; __global__ void __launch_bounds__(NTHR) fwd_kernel(Args args) {
;     ...
;                     if (idx >= 1024) break;
;     ...
;         if (multi && ph + 1 < hi_ph) { if (lo == 0x7fffff01) cg::this_grid().sync();   else xcd_barrier(bar); }
.LBB0_307:
	s_setprio 0
	v_readlane_b32 s74, v255, 13
	v_readlane_b32 s75, v255, 14
	s_branch .LBB0_499
